# one static s_setprio 1 for waves 4-7 at kernel entry (on top of the flip-free K-loops)
# baseline (speedup 1.0000x reference)
; #define LAS __attribute__((address_space(3)))
; __device__ __forceinline__ XcdBarrier xcd_barrier_post(unsigned* bar, volatile LAS unsigned* st) {
;     XcdBarrier b; b.bar = bar; b.x = xb_xcc_id(); b.st = st;
;     if (threadIdx.x == 0) (void)xb_add(&bar[XB_XCNT(b.x)], 1u);
;     return b;
; }
; __device__ __forceinline__ void xcd_barrier_complete(unsigned* bar, unsigned x, unsigned& nloc, unsigned& nx) {
;     const unsigned G = gridDim.x * gridDim.y * gridDim.z;
;     unsigned sum, cnt, mine, sp = 0u;
;     for (;;) {
;         sum = 0u; cnt = 0u; mine = 0u;
; #pragma unroll
;         for (unsigned j = 0; j < 16; ++j) { const unsigned c = xb_ld(&bar[XB_XCNT(j)]); sum += c; cnt += (c > 0u) ? 1u : 0u; mine = (j == x) ? c : mine; }
;         if (sum == G) break;
;         __builtin_amdgcn_s_sleep(1);
;         if ((++sp & 255u) == 0u) { if (xb_ld(&bar[XB_TMO])) break; if (sp > XB_SPIN_CAP) { atomicAdd(&bar[XB_TMO], 1u); break; } }
;     }
;     nloc = mine > 0u ? mine : 1u; nx = cnt > 0u ? cnt : 1u;
; }
; __device__ __forceinline__ void xcd_barrier(const XcdBarrier& b) {
;     asm volatile("s_waitcnt vmcnt(0)" ::: "memory");
;     __syncthreads();
;     if (threadIdx.x == 0) {
;         unsigned* bar = b.bar;
;         __builtin_amdgcn_s_waitcnt(0);
;         unsigned nloc = b.st[0], nx = b.st[1];
;         if (nloc == 0u) { xcd_barrier_complete(bar, b.x, nloc, nx); b.st[0] = nloc; b.st[1] = nx; }
;         const unsigned old = xb_add(&bar[XB_XSUB(b.x)], 1u);
;         const unsigned gen = old / nloc;
;         if (old + 1u == (gen + 1u) * nloc) {
;             __builtin_amdgcn_fence(__ATOMIC_RELEASE, "agent");
;             asm volatile("s_waitcnt vmcnt(0)" ::: "memory");
;             const unsigned og = xb_add(&bar[XB_TOP], 1u);
;             const unsigned tg = og / nx;
;             if (og + 1u == (tg + 1u) * nx) xb_add(&bar[XB_TOPGEN], 1u);
;             else XB_SPIN(xb_ld(&bar[XB_TOPGEN]) == tg, bar);
;             __builtin_amdgcn_fence(__ATOMIC_ACQUIRE, "agent");
;             xb_add(&bar[XB_XGEN(b.x)], 1u);
; __device__ __forceinline__ void norm_phase(const float* xl, const float* xc, bf16_t* HN, const float* gain, const float* mods_l, int sidx, int nrows, int lane, int gw, int NGW,
;                                            float* ctxr_rw, const float* part, int npart, const float* pgate) {
;     const bool blocked = (ML % NGW) == 0;
.LBB0_5:
	s_or_b64 exec, exec, s[2:3]
	s_cmp_ge_i32 s70, s71
	s_cbranch_scc1 .LBB0_601
	v_readlane_b32 s8, v253, 0
	s_lshl_b32 s5, s8, 9
	s_cmpk_lg_i32 s8, 0x100
	s_cselect_b64 s[2:3], -1, 0
	v_readlane_b32 s9, v253, 1
	v_writelane_b32 v253, s2, 8
	s_lshl_b32 s15, s8, 3
	v_lshrrev_b32_e32 v2, 20, v0
	v_writelane_b32 v253, s3, 9
	s_ashr_i32 s2, s8, 31
	v_writelane_b32 v253, s2, 10
	s_add_i32 s3, s15, 0x7fff
	s_add_i32 s2, s15, 0x7ff
	s_add_u32 s10, s68, 0x800200
	s_addc_u32 s11, s69, 0
	s_add_u32 s46, s68, 0x800400
	s_addc_u32 s47, s69, 0
	s_add_u32 s48, s68, 0x800500
	s_addc_u32 s49, s69, 0
	s_add_u32 s50, s68, 0x800600
	v_writelane_b32 v253, s10, 11
	s_addc_u32 s51, s69, 0
	v_lshrrev_b32_e32 v0, 10, v0
	v_writelane_b32 v253, s11, 12
	s_add_u32 s10, s68, 0x800700
	s_addc_u32 s11, s69, 0
	v_writelane_b32 v253, s10, 13
	v_or_b32_e32 v0, v0, v2
	v_mov_b32_e32 v49, 0
	v_writelane_b32 v253, s11, 14
	s_add_u32 s10, s68, 0x800800
	s_addc_u32 s11, s69, 0
	v_writelane_b32 v253, s10, 15
	v_mov_b32_e32 v221, 0x3ecc95a3
	v_mov_b32_e32 v223, 0x358637bd
	v_writelane_b32 v253, s11, 16
	s_add_u32 s10, s68, 0x800900
	s_addc_u32 s11, s69, 0
	v_writelane_b32 v253, s10, 17
	v_mov_b32_e32 v230, 1
	v_mov_b32_e32 v174, 0x3f317218
	v_writelane_b32 v253, s11, 18
	s_add_u32 s10, s68, 0x800a00
	s_addc_u32 s11, s69, 0
	v_writelane_b32 v253, s10, 19
	v_mov_b32_e32 v249, 0x7f800000
	v_mov_b32_e32 v250, 0x7fc00000
	v_writelane_b32 v253, s11, 20
	s_add_u32 s10, s68, 0x800b00
	s_addc_u32 s11, s69, 0
	v_writelane_b32 v253, s10, 21
	v_mov_b32_e32 v251, 0xff800000
	v_mov_b32_e32 v231, 0xff
	v_writelane_b32 v253, s11, 22
	s_add_u32 s10, s68, 0x800c00
	s_addc_u32 s11, s69, 0
	v_writelane_b32 v253, s10, 23
	v_mov_b32_e32 v232, 0xfff
	v_mov_b32_e32 v233, 0xf149f2ca
	v_writelane_b32 v253, s11, 24
	s_add_u32 s10, s68, 0x800d00
	s_addc_u32 s11, s69, 0
	v_writelane_b32 v253, s10, 25
	v_mov_b32_e32 v252, 0x14400
	v_mov_b32_e32 v244, 0x19e00
	v_writelane_b32 v253, s11, 26
	s_add_u32 s10, s68, 0x800e00
	s_addc_u32 s11, s69, 0
	v_writelane_b32 v253, s10, 27
	v_mov_b32_e32 v245, 0x1a700
	v_mov_b32_e32 v246, 0x1b900
	v_writelane_b32 v253, s11, 28
	s_add_u32 s10, s68, 0x800f00
	s_addc_u32 s11, s69, 0
	v_writelane_b32 v253, s10, 29
	v_mov_b32_e32 v247, 0x1c200
	v_mov_b32_e32 v248, 0x1cb00
	v_writelane_b32 v253, s11, 30
	s_add_u32 s10, s68, 0x801000
	s_addc_u32 s11, s69, 0
	v_writelane_b32 v253, s10, 31
	s_mov_b32 s58, 0x48000
	s_mov_b32 s57, 0
	v_writelane_b32 v253, s11, 32
	s_add_u32 s10, s68, 0x801100
	s_addc_u32 s11, s69, 0
	v_writelane_b32 v253, s10, 33
	s_mov_b32 s14, 0xbfb8aa3b
	s_nop 0
	v_writelane_b32 v253, s11, 34
	s_add_u32 s10, s68, 0x801200
	s_addc_u32 s11, s69, 0
	v_writelane_b32 v253, s10, 35
	s_nop 1
	v_writelane_b32 v253, s11, 36
	s_add_u32 s10, s68, 0x801300
	s_addc_u32 s11, s69, 0
	v_writelane_b32 v253, s10, 37
	s_cmp_eq_u32 s6, 15
	s_nop 0
	v_writelane_b32 v253, s11, 38
	s_cselect_b64 s[10:11], -1, 0
	v_writelane_b32 v253, s10, 39
	s_cmp_eq_u32 s6, 14
	s_nop 0
	v_writelane_b32 v253, s11, 40
	s_cselect_b64 s[10:11], -1, 0
	v_writelane_b32 v253, s10, 41
	s_cmp_eq_u32 s6, 13
	s_nop 0
	v_writelane_b32 v253, s11, 42
	s_cselect_b64 s[10:11], -1, 0
	v_writelane_b32 v253, s10, 43
	s_cmp_eq_u32 s6, 12
	s_nop 0
	v_writelane_b32 v253, s11, 44
	s_cselect_b64 s[10:11], -1, 0
	v_writelane_b32 v253, s10, 45
	s_cmp_eq_u32 s6, 11
	s_nop 0
	v_writelane_b32 v253, s11, 46
	s_cselect_b64 s[10:11], -1, 0
	v_writelane_b32 v253, s10, 47
	s_cmp_eq_u32 s6, 10
	s_nop 0
	v_writelane_b32 v253, s11, 48
	s_cselect_b64 s[10:11], -1, 0
	v_writelane_b32 v253, s10, 49
	s_cmp_eq_u32 s6, 9
	s_nop 0
	v_writelane_b32 v253, s11, 50
	s_cselect_b64 s[10:11], -1, 0
	v_writelane_b32 v253, s10, 51
	s_cmp_eq_u32 s6, 8
	s_nop 0
	v_writelane_b32 v253, s11, 52
	s_cselect_b64 s[10:11], -1, 0
	v_writelane_b32 v253, s10, 53
	s_cmp_eq_u32 s6, 7
	s_nop 0
	v_writelane_b32 v253, s11, 54
	s_cselect_b64 s[10:11], -1, 0
	v_writelane_b32 v253, s10, 55
	s_cmp_eq_u32 s6, 6
	s_nop 0
	v_writelane_b32 v253, s11, 56
	s_cselect_b64 s[10:11], -1, 0
	v_writelane_b32 v253, s10, 57
	s_cmp_eq_u32 s6, 5
	s_nop 0
	v_writelane_b32 v253, s11, 58
	s_cselect_b64 s[10:11], -1, 0
	v_writelane_b32 v253, s10, 59
	s_cmp_eq_u32 s6, 4
	s_nop 0
	v_writelane_b32 v253, s11, 60
	s_cselect_b64 s[10:11], -1, 0
	v_writelane_b32 v253, s10, 61
	s_cmp_eq_u32 s6, 3
	s_nop 0
	v_writelane_b32 v253, s11, 62
	s_cselect_b64 s[10:11], -1, 0
	v_writelane_b32 v253, s10, 63
	s_cmp_eq_u32 s6, 2
	s_nop 0
	v_writelane_b32 v254, s11, 0
	s_cselect_b64 s[10:11], -1, 0
	v_writelane_b32 v254, s10, 1
	s_cmp_eq_u32 s6, 1
	s_nop 0
	v_writelane_b32 v254, s11, 2
	s_cselect_b64 s[10:11], -1, 0
	v_writelane_b32 v254, s10, 3
	s_cmp_eq_u32 s6, 0
	s_nop 0
	v_writelane_b32 v254, s11, 4
	s_cselect_b64 s[10:11], -1, 0
	s_lshl_b32 s4, s6, 8
	s_add_u32 s0, s0, s4
	s_addc_u32 s1, s1, 0
	v_writelane_b32 v254, s10, 5
	s_add_u32 s6, s0, 0x1400
	s_addc_u32 s7, s1, 0
	v_writelane_b32 v254, s11, 6
	v_writelane_b32 v254, s6, 7
	s_add_u32 s0, s0, 0x2400
	s_addc_u32 s1, s1, 0
	v_writelane_b32 v254, s7, 8
	v_writelane_b32 v254, s0, 9
	s_nop 1
	v_writelane_b32 v254, s1, 10
	s_add_u32 s0, s68, 0x803400
	s_addc_u32 s1, s69, 0
	v_writelane_b32 v254, s0, 11
	s_nop 1
	v_writelane_b32 v254, s1, 12
	s_add_u32 s0, s68, 0x803500
	s_addc_u32 s1, s69, 0
	s_abs_i32 s4, s8
	v_cvt_f32_u32_e32 v1, s4
	v_writelane_b32 v254, s0, 13
	s_mov_b32 s69, s5
	s_movk_i32 s68, 0x23f
	v_rcp_iflag_f32_e32 v1, v1
	v_writelane_b32 v254, s1, 14
	s_sub_i32 s0, 0, s4
	v_mul_f32_e32 v1, 0x4f7ffffe, v1
	v_cvt_u32_f32_e32 v1, v1
	s_nop 0
	v_readfirstlane_b32 s1, v1
	s_mul_i32 s0, s0, s1
	s_mul_hi_u32 s0, s1, s0
	s_add_i32 s0, s1, s0
	v_writelane_b32 v254, s0, 15
	s_lshr_b32 s0, s0, 26
	s_mul_i32 s0, s0, s4
	s_sub_i32 s0, 64, s0
	s_sub_i32 s1, s0, s4
	s_cmp_ge_u32 s0, s4
	s_cselect_b32 s0, s1, s0
	s_sub_i32 s1, s0, s4
	s_cmp_ge_u32 s0, s4
	s_cselect_b32 s0, s1, s0
	s_abs_i32 s33, s15
	v_cvt_f32_u32_e32 v1, s33
	v_writelane_b32 v254, s4, 16
	v_readlane_b32 s4, v253, 2
	v_readlane_b32 s5, v253, 3
	v_rcp_iflag_f32_e32 v1, v1
	s_load_dword s1, s[4:5], 0xf0
	v_writelane_b32 v254, s0, 17
	s_mul_i32 s0, s9, s8
	v_mul_f32_e32 v1, 0x4f7ffffe, v1
	v_cvt_u32_f32_e32 v1, v1
	s_waitcnt lgkmcnt(0)
; #define LAS __attribute__((address_space(3)))
; __device__ __forceinline__ void norm_phase(const float* xl, const float* xc, bf16_t* HN, const float* gain, const float* mods_l, int sidx, int nrows, int lane, int gw, int NGW,
;                                            float* ctxr_rw, const float* part, int npart, const float* pgate) {
;     const bool blocked = (ML % NGW) == 0;
;     const int rpw = blocked ? ML / NGW : (ML + NGW - 1) / NGW;
;     const int nctx = nrows > ML ? (nrows - ML + NGW - 1) / NGW : 0;
; __global__ void __launch_bounds__(512, 2) fwd_kernel(Args a) {
;     ...
;     volatile LAS unsigned* bst = (volatile LAS unsigned*)(lds + 131072 + 64);
;     if (threadIdx.x < 4) bst[threadIdx.x] = 0u;
;     __syncthreads();
;     const XcdBarrier bar = xcd_barrier_post((unsigned*)(a.ws + WS_BAR), bst);
	s_mul_i32 s55, s0, s1
	s_movk_i32 s0, 0x3ff
	v_and_or_b32 v0, v0, s0, v220
	s_sub_i32 s0, 0, s33
	v_readfirstlane_b32 s1, v1
	s_mul_i32 s0, s0, s1
	s_mul_hi_u32 s0, s1, s0
	s_add_i32 s52, s1, s0
	s_lshr_b32 s0, s52, 17
	s_mul_i32 s0, s0, s33
	s_sub_i32 s0, 0x8000, s0
	s_ashr_i32 s4, s15, 31
	s_sub_i32 s1, s0, s33
	s_cmp_ge_u32 s0, s33
	s_cselect_b32 s0, s1, s0
	s_sub_i32 s1, s0, s33
	s_cmp_ge_u32 s0, s33
	s_cselect_b32 s0, s1, s0
	s_cmp_lg_u32 s0, 0
	s_cselect_b64 s[0:1], -1, 0
	v_writelane_b32 v254, s0, 18
	v_mbcnt_lo_u32_b32 v1, -1, 0
	s_nop 0
	v_writelane_b32 v254, s1, 19
	s_and_b64 s[0:1], s[0:1], exec
	s_cselect_b32 s0, s3, 0x8000
	s_abs_i32 s1, s0
	s_mul_hi_u32 s3, s1, s52
	s_mul_i32 s5, s3, s33
	s_sub_i32 s1, s1, s5
	s_ashr_i32 s0, s0, 31
	s_xor_b32 s0, s0, s4
	s_add_i32 s5, s3, 1
	s_sub_i32 s6, s1, s33
	s_cmp_ge_u32 s1, s33
	s_cselect_b32 s3, s5, s3
	s_cselect_b32 s1, s6, s1
	s_add_i32 s5, s3, 1
	s_cmp_ge_u32 s1, s33
	s_cselect_b32 s1, s5, s3
	s_xor_b32 s1, s1, s0
	s_sub_i32 s0, s1, s0
	s_sub_i32 s1, 0xfffff801, s15
	s_max_i32 s1, s2, s1
	v_writelane_b32 v254, s0, 20
	s_ashr_i32 s0, s2, 31
	s_mul_hi_u32 s2, s1, s52
	s_mul_i32 s3, s2, s33
	s_sub_i32 s1, s1, s3
	s_xor_b32 s0, s0, s4
	s_add_i32 s3, s2, 1
	s_sub_i32 s4, s1, s33
	s_cmp_ge_u32 s1, s33
	s_cselect_b32 s2, s3, s2
	s_cselect_b32 s1, s4, s1
	s_add_i32 s3, s2, 1
	s_cmp_ge_u32 s1, s33
	s_cselect_b32 s1, s3, s2
	s_xor_b32 s1, s1, s0
	s_sub_i32 s0, s1, s0
	v_writelane_b32 v254, s0, 21
	s_lshl_b32 s0, s8, 1
	v_writelane_b32 v254, s0, 22
	s_lshl_b32 s0, s8, 7
	v_writelane_b32 v254, s0, 23
	s_lshl_b32 s0, s8, 5
	v_writelane_b32 v254, s0, 24
	s_add_i32 s0, 0, 0x20400
	v_writelane_b32 v254, s0, 25
	s_add_i32 s0, 0, 0x11000
	v_writelane_b32 v254, s0, 26
	s_add_i32 s0, 0, 0x20040
	v_writelane_b32 v254, s0, 27
	s_add_i32 s0, 0, 0x20044
	v_writelane_b32 v254, s0, 28
	v_cmp_eq_u32_e64 s[0:1], 0, v0
	v_mbcnt_hi_u32_b32 v222, -1, v1
	v_and_b32_e32 v1, 64, v222
	v_writelane_b32 v254, s0, 29
	v_xor_b32_e32 v226, 32, v222
	v_add_u32_e32 v227, 64, v1
	v_writelane_b32 v254, s1, 30
	v_writelane_b32 v254, s54, 31
	v_writelane_b32 v254, s69, 32
	v_writelane_b32 v254, s46, 33
	s_movk_i32 s4, 0x6000
	s_movk_i32 s5, 0x90
	v_writelane_b32 v254, s47, 34
	v_writelane_b32 v254, s48, 35
	s_mov_b64 s[0:1], 0x80
	s_nop 0
	v_writelane_b32 v254, s49, 36
	v_writelane_b32 v254, s50, 37
	s_nop 1
	v_writelane_b32 v254, s51, 38
	v_writelane_b32 v254, s55, 39
	v_writelane_b32 v254, s52, 40
	v_readfirstlane_b32 s98, v220
	s_cmpk_lt_u32 s98, 0x100
	s_cbranch_scc1 .Lprio_done
	s_setprio 1
.Lprio_done:
	s_branch .LBB0_11
